# attention: unmasked tile-loop variant for all-valid stages + V fragment LDS reads hoisted to loop top
# baseline (speedup 1.0000x reference)
; #define LAS __attribute__((address_space(3)))
; __device__ __forceinline__ void attn_phase(LAS unsigned char* lds, bf16* qkv, const float* qgain, const float* kgain, const float* sink, const float* ropetab, int G, int bid) {
;     ...
;             const int msg = (type == 0) ? 1 : (type == 2 ? -1 : 0);
; #pragma unroll 1
;             for (int T = 0; T < 4; ++T) {
;                 bf16x8 kf[2][2];
; #pragma unroll
;                 for (int sub = 0; sub < 2; ++sub)
; #pragma unroll
;                     for (int dh = 0; dh < 2; ++dh) kf[sub][dh] = *(const LAS bf16x8*)(Ks + (T * 32 + sub * 16 + fr) * 160 + dh * 64 + fq * 16);
;                 bf16x8 pb[4];
; #pragma unroll
;                 for (int qi = 0; qi < 4; ++qi) {
;                     f32x4 s0 = (f32x4){0.f, 0.f, 0.f, 0.f}, s1 = (f32x4){0.f, 0.f, 0.f, 0.f};
;                     s0 = __builtin_amdgcn_mfma_f32_16x16x32_bf16(kf[0][0], qf[qi][0], s0, 0, 0, 0);
;                     s0 = __builtin_amdgcn_mfma_f32_16x16x32_bf16(kf[0][1], qf[qi][1], s0, 0, 0, 0);
;                     s1 = __builtin_amdgcn_mfma_f32_16x16x32_bf16(kf[1][0], qf[qi][0], s1, 0, 0, 0);
;                     s1 = __builtin_amdgcn_mfma_f32_16x16x32_bf16(kf[1][1], qf[qi][1], s1, 0, 0, 0);
;                     const int mbase = msg * (T * 32 + fq * 4 - (whalf * 64 + qi * 16 + fr));
;                     float p0[4], p1[4];
; #pragma unroll
;                     for (int j = 0; j < 4; ++j) {
;                         const float e0 = __builtin_amdgcn_exp2f(s0[j] - Mshift), e1 = __builtin_amdgcn_exp2f(s1[j] - Mshift);
;                         p0[j] = (mbase + msg * j >= 0) ? e0 : 0.f;
;                         p1[j] = (mbase + msg * (16 + j) >= 0) ? e1 : 0.f;
;                     }
;                     lsum[qi] += (p0[0] + p0[1]) + (p0[2] + p0[3]) + (p1[0] + p1[1]) + (p1[2] + p1[3]);
;                     u32x4 w; w.x = cvt_pk_bf16(p0[0], p0[1]); w.y = cvt_pk_bf16(p0[2], p0[3]); w.z = cvt_pk_bf16(p1[0], p1[1]); w.w = cvt_pk_bf16(p1[2], p1[3]);
;                     pb[qi] = __builtin_bit_cast(bf16x8, w);
;                 }
.LBB0_586:
	s_xor_b64 s[36:37], s[4:5], -1
	s_cmp_eq_u32 s18, 2
	s_waitcnt lgkmcnt(0)
	s_barrier
	s_cselect_b64 s[0:1], -1, 0
	s_cmp_lg_u32 s18, 0
	v_cndmask_b32_e64 v3, 0, -1, s[0:1]
	s_cselect_b64 vcc, -1, 0
	s_mov_b32 s4, 0
	v_cndmask_b32_e32 v3, 1, v3, vcc
	v_mov_b32_e32 v151, v185
	v_mov_b32_e32 v153, v187
	s_bitcmp1_b32 s18, 0
	s_cbranch_scc1 .LattU_587
.LBB0_587:
	ds_read_b128 v[124:127], v153
	ds_read_b128 v[128:131], v153 offset:64
	ds_read_b128 v[132:135], v153 offset:2560
	ds_read_b128 v[136:139], v153 offset:2624
	v_add_u32_e32 v240, s4, v186
	ds_read2_b64 v[224:227], v240 offset1:4
	v_add_u32_e32 v241, 0x1000, v240
	ds_read2_b64 v[228:231], v241 offset0:32 offset1:36
	v_add_u32_e32 v241, 0x2000, v240
	ds_read2_b64 v[232:235], v241 offset0:64 offset1:68
	v_add_u32_e32 v241, 0x3000, v240
	ds_read2_b64 v[236:239], v241 offset0:96 offset1:100
	v_add_u32_e32 v205, v151, v141
	s_waitcnt lgkmcnt(7)
	v_mfma_f32_16x16x32_bf16 v[116:119], v[124:127], v[108:111], 0
	v_add_u32_e32 v206, v151, v140
	v_mul_lo_u32 v201, v205, v3
	v_mul_lo_u32 v197, v206, v3
	s_waitcnt lgkmcnt(5)
	v_mfma_f32_16x16x32_bf16 v[120:123], v[132:135], v[108:111], 0
	v_cmp_lt_i32_e64 s[40:41], -1, v201
	v_cmp_lt_i32_e64 s[0:1], -1, v197
	v_add_u32_e32 v153, 0x1400, v153
	v_mfma_f32_16x16x32_bf16 v[116:119], v[128:131], v[112:115], v[116:119]
	s_waitcnt lgkmcnt(4)
	v_mfma_f32_16x16x32_bf16 v[120:123], v[136:139], v[112:115], v[120:123]
	s_nop 5
	v_sub_f32_e32 v116, v116, v174
	v_exp_f32_e32 v191, v116
	v_sub_f32_e32 v116, v120, v174
	v_exp_f32_e32 v192, v116
	v_sub_f32_e32 v116, v117, v174
	v_exp_f32_e32 v194, v116
	v_sub_f32_e32 v116, v121, v174
	v_exp_f32_e32 v196, v116
	v_sub_f32_e32 v116, v118, v174
	v_exp_f32_e32 v198, v116
	v_sub_f32_e32 v116, v122, v174
	v_exp_f32_e32 v200, v116
	v_sub_f32_e32 v116, v119, v174
	v_exp_f32_e32 v202, v116
	v_sub_f32_e32 v116, v123, v174
	v_exp_f32_e32 v204, v116
	v_mfma_f32_16x16x32_bf16 v[116:119], v[124:127], v[68:71], 0
	v_mfma_f32_16x16x32_bf16 v[120:123], v[132:135], v[68:71], 0
	v_mfma_f32_16x16x32_bf16 v[116:119], v[128:131], v[100:103], v[116:119]
	v_mfma_f32_16x16x32_bf16 v[120:123], v[136:139], v[100:103], v[120:123]
	s_nop 6
	v_sub_f32_e32 v116, v116, v174
	v_sub_f32_e32 v120, v120, v174
	v_exp_f32_e32 v116, v116
	v_exp_f32_e32 v193, v120
	v_sub_f32_e32 v120, v121, v174
	v_sub_f32_e32 v117, v117, v174
	v_exp_f32_e32 v195, v120
	v_sub_f32_e32 v120, v122, v174
	v_exp_f32_e32 v117, v117
	v_exp_f32_e32 v199, v120
	v_sub_f32_e32 v120, v123, v174
	v_exp_f32_e32 v203, v120
	v_add_u32_e32 v120, 16, v206
	v_mul_lo_u32 v120, v120, v3
	v_cndmask_b32_e64 v121, 0, v116, s[40:41]
	v_add_u32_e32 v116, v201, v3
	v_cmp_lt_i32_e32 vcc, -1, v120
	v_cndmask_b32_e64 v120, 0, v191, s[0:1]
	v_cndmask_b32_e64 v123, 0, v193, s[0:1]
	v_cmp_lt_i32_e64 s[0:1], -1, v116
	v_add_u32_e32 v191, v197, v3
	v_add_u32_e32 v116, 17, v206
	v_cndmask_b32_e64 v193, 0, v117, s[0:1]
	v_add_u32_e32 v117, 17, v205
	v_sub_f32_e32 v118, v118, v174
	v_cndmask_b32_e32 v122, 0, v192, vcc
	v_cmp_lt_i32_e32 vcc, -1, v191
	v_mul_lo_u32 v117, v117, v3
	v_mul_lo_u32 v116, v116, v3
	v_exp_f32_e32 v118, v118
	v_cndmask_b32_e32 v192, 0, v194, vcc
	v_cmp_lt_i32_e32 vcc, -1, v116
	v_cmp_lt_i32_e64 s[0:1], -1, v117
	v_add_u32_e32 v116, 2, v206
	v_add_u32_e32 v117, 2, v205
	v_mul_lo_u32 v117, v117, v3
	v_mul_lo_u32 v116, v116, v3
	v_sub_f32_e32 v119, v119, v174
	v_cndmask_b32_e64 v195, 0, v195, s[0:1]
	v_cndmask_b32_e32 v194, 0, v196, vcc
	v_cmp_lt_i32_e32 vcc, -1, v116
	v_cmp_lt_i32_e64 s[0:1], -1, v117
	v_add_u32_e32 v116, 18, v206
	v_add_u32_e32 v117, 18, v205
	v_exp_f32_e32 v119, v119
	v_mul_lo_u32 v117, v117, v3
	v_mul_lo_u32 v116, v116, v3
	v_cndmask_b32_e64 v197, 0, v118, s[0:1]
	v_cndmask_b32_e32 v196, 0, v198, vcc
	v_cmp_lt_i32_e32 vcc, -1, v116
	v_cmp_lt_i32_e64 s[0:1], -1, v117
	v_add_u32_e32 v116, 3, v206
	v_add_u32_e32 v117, 3, v205
	v_mul_lo_u32 v117, v117, v3
	v_mul_lo_u32 v116, v116, v3
	v_cndmask_b32_e64 v199, 0, v199, s[0:1]
	v_cndmask_b32_e32 v198, 0, v200, vcc
	v_cmp_lt_i32_e32 vcc, -1, v116
	v_cmp_lt_i32_e64 s[0:1], -1, v117
	v_add_u32_e32 v116, 19, v206
	v_add_u32_e32 v117, 19, v205
	v_cndmask_b32_e64 v201, 0, v119, s[0:1]
	v_cndmask_b32_e32 v200, 0, v202, vcc
	v_mul_lo_u32 v117, v117, v3
	v_mul_lo_u32 v116, v116, v3
	v_cmp_lt_i32_e32 vcc, -1, v116
	v_cmp_lt_i32_e64 s[0:1], -1, v117
	v_pk_add_f32 v[116:117], v[120:121], v[192:193]
	v_pk_add_f32 v[118:119], v[196:197], v[200:201]
	v_cndmask_b32_e64 v203, 0, v203, s[0:1]
	v_cndmask_b32_e32 v202, 0, v204, vcc
	v_pk_add_f32 v[116:117], v[116:117], v[118:119]
	v_pk_add_f32 v[118:119], v[122:123], v[194:195]
	s_nop 0
	v_pk_add_f32 v[116:117], v[116:117], v[118:119]
	v_pk_add_f32 v[118:119], v[198:199], v[202:203]
	s_nop 0
	v_pk_add_f32 v[204:205], v[118:119], v[116:117]
	v_cvt_pk_bf16_f32 v116, v120, v192
	v_cvt_pk_bf16_f32 v118, v122, v194
	v_cvt_pk_bf16_f32 v120, v121, v193
	v_cvt_pk_bf16_f32 v122, v123, v195
	v_mfma_f32_16x16x32_bf16 v[192:195], v[124:127], v[60:63], 0
	v_cvt_pk_bf16_f32 v117, v196, v200
	v_cvt_pk_bf16_f32 v119, v198, v202
	v_cvt_pk_bf16_f32 v121, v197, v201
	v_mfma_f32_16x16x32_bf16 v[124:127], v[124:127], v[52:55], 0
	v_cvt_pk_bf16_f32 v123, v199, v203
	v_pk_add_f32 v[170:171], v[170:171], v[204:205]
	v_mfma_f32_16x16x32_bf16 v[198:201], v[128:131], v[64:67], v[192:195]
	v_mfma_f32_16x16x32_bf16 v[128:131], v[128:131], v[56:59], v[124:127]
	v_mfma_f32_16x16x32_bf16 v[124:127], v[132:135], v[52:55], 0
	s_nop 5
	v_sub_f32_e32 v191, v198, v174
	v_exp_f32_e32 v198, v191
	v_mfma_f32_16x16x32_bf16 v[192:195], v[132:135], v[60:63], 0
	v_mfma_f32_16x16x32_bf16 v[132:135], v[136:139], v[56:59], v[124:127]
; #define LAS __attribute__((address_space(3)))
; __device__ __forceinline__ void attn_phase(LAS unsigned char* lds, bf16* qkv, const float* qgain, const float* kgain, const float* sink, const float* ropetab, int G, int bid) {
;     ...
;                     const int mbase = msg * (T * 32 + fq * 4 - (whalf * 64 + qi * 16 + fr));
;                     float p0[4], p1[4];
; #pragma unroll
;                     for (int j = 0; j < 4; ++j) {
;                         const float e0 = __builtin_amdgcn_exp2f(s0[j] - Mshift), e1 = __builtin_amdgcn_exp2f(s1[j] - Mshift);
;                         p0[j] = (mbase + msg * j >= 0) ? e0 : 0.f;
;                         p1[j] = (mbase + msg * (16 + j) >= 0) ? e1 : 0.f;
;                     }
;                     lsum[qi] += (p0[0] + p0[1]) + (p0[2] + p0[3]) + (p1[0] + p1[1]) + (p1[2] + p1[3]);
;                     u32x4 w; w.x = cvt_pk_bf16(p0[0], p0[1]); w.y = cvt_pk_bf16(p0[2], p0[3]); w.z = cvt_pk_bf16(p1[0], p1[1]); w.w = cvt_pk_bf16(p1[2], p1[3]);
;                     pb[qi] = __builtin_bit_cast(bf16x8, w);
;                 }
; #pragma unroll
;                 for (int dt = 0; dt < 4; ++dt) {
;                     const LAS unsigned char* vp = Vt + (dt * 16 + fr) * 272 + (T * 32 + fq * 4) * 2;
;                     const u32x2 lo = *(const LAS u32x2*)vp, hi = *(const LAS u32x2*)(vp + 32);
;                     u32x4 w; w.x = lo[0]; w.y = lo[1]; w.z = hi[0]; w.w = hi[1];
;                     const bf16x8 vf = __builtin_bit_cast(bf16x8, w);
; #pragma unroll
;                     for (int qi = 0; qi < 4; ++qi) o[dt][qi] = __builtin_amdgcn_mfma_f32_16x16x32_bf16(vf, pb[qi], o[dt][qi], 0, 0, 0);
;                 }
	v_mfma_f32_16x16x32_bf16 v[202:205], v[136:139], v[64:67], v[192:195]
	s_nop 1
	v_sub_f32_e32 v124, v128, v174
	v_exp_f32_e32 v136, v124
	s_nop 2
	v_sub_f32_e32 v124, v132, v174
	v_exp_f32_e32 v132, v124
	v_sub_f32_e32 v124, v129, v174
	v_exp_f32_e32 v129, v124
	v_sub_f32_e32 v124, v133, v174
	v_sub_f32_e32 v191, v202, v174
	v_exp_f32_e32 v128, v124
	v_sub_f32_e32 v124, v130, v174
	v_exp_f32_e32 v197, v191
	v_sub_f32_e32 v191, v199, v174
	v_exp_f32_e32 v127, v124
	v_sub_f32_e32 v124, v134, v174
	v_exp_f32_e32 v196, v191
	v_sub_f32_e32 v191, v203, v174
	v_exp_f32_e32 v126, v124
	v_sub_f32_e32 v124, v131, v174
	v_add_u32_e32 v199, v147, v151
	v_exp_f32_e32 v195, v191
	v_sub_f32_e32 v191, v200, v174
	v_exp_f32_e32 v125, v124
	v_sub_f32_e32 v124, v135, v174
	v_add_u32_e32 v200, v146, v151
	v_add_u32_e32 v134, 16, v199
	v_mul_lo_u32 v135, v199, v3
	v_add_u32_e32 v133, 16, v200
	v_mul_lo_u32 v137, v200, v3
	v_cmp_lt_i32_e64 s[0:1], -1, v135
	v_mul_lo_u32 v134, v134, v3
	v_cmp_lt_i32_e32 vcc, -1, v137
	v_cndmask_b32_e64 v131, 0, v136, s[0:1]
	v_mul_lo_u32 v133, v133, v3
	v_cmp_lt_i32_e64 s[0:1], -1, v134
	v_add_u32_e32 v134, v135, v3
	v_cndmask_b32_e32 v130, 0, v198, vcc
	v_cmp_lt_i32_e32 vcc, -1, v133
	v_cndmask_b32_e64 v133, 0, v132, s[0:1]
	v_add_u32_e32 v135, v137, v3
	v_cmp_lt_i32_e64 s[0:1], -1, v134
	v_cndmask_b32_e32 v132, 0, v197, vcc
	v_cmp_lt_i32_e32 vcc, -1, v135
	v_cndmask_b32_e64 v135, 0, v129, s[0:1]
	v_add_u32_e32 v129, 17, v200
	v_add_u32_e32 v136, 17, v199
	v_mul_lo_u32 v129, v129, v3
	v_cndmask_b32_e32 v134, 0, v196, vcc
	v_mul_lo_u32 v136, v136, v3
	v_cmp_lt_i32_e32 vcc, -1, v129
	v_add_u32_e32 v129, 2, v199
	v_exp_f32_e32 v194, v191
	v_cmp_lt_i32_e64 s[0:1], -1, v136
	v_mul_lo_u32 v129, v129, v3
	v_sub_f32_e32 v191, v204, v174
	v_cndmask_b32_e64 v137, 0, v128, s[0:1]
	v_add_u32_e32 v128, 2, v200
	v_cmp_lt_i32_e64 s[0:1], -1, v129
	v_add_u32_e32 v138, 18, v199
	v_exp_f32_e32 v193, v191
	v_mul_lo_u32 v128, v128, v3
	v_cndmask_b32_e64 v129, 0, v127, s[0:1]
	v_add_u32_e32 v127, 18, v200
	v_mul_lo_u32 v138, v138, v3
	v_sub_f32_e32 v191, v201, v174
	v_cndmask_b32_e32 v136, 0, v195, vcc
	v_cmp_lt_i32_e32 vcc, -1, v128
	v_mul_lo_u32 v127, v127, v3
	v_cmp_lt_i32_e64 s[0:1], -1, v138
	v_exp_f32_e32 v192, v191
	v_cndmask_b32_e32 v128, 0, v194, vcc
	v_cmp_lt_i32_e32 vcc, -1, v127
	v_cndmask_b32_e64 v139, 0, v126, s[0:1]
	v_add_u32_e32 v126, 3, v200
	v_add_u32_e32 v127, 3, v199
	v_sub_f32_e32 v191, v205, v174
	v_exp_f32_e32 v124, v124
	v_mul_lo_u32 v127, v127, v3
	v_mul_lo_u32 v126, v126, v3
	v_exp_f32_e32 v191, v191
	v_cndmask_b32_e32 v138, 0, v193, vcc
	v_cmp_lt_i32_e32 vcc, -1, v126
	v_cmp_lt_i32_e64 s[0:1], -1, v127
	v_add_u32_e32 v126, 19, v199
	v_mul_lo_u32 v126, v126, v3
	v_cndmask_b32_e64 v193, 0, v125, s[0:1]
	v_add_u32_e32 v125, 19, v200
	v_cndmask_b32_e32 v192, 0, v192, vcc
	v_mul_lo_u32 v125, v125, v3
	v_cmp_lt_i32_e64 s[0:1], -1, v126
	v_cmp_lt_i32_e32 vcc, -1, v125
	v_pk_add_f32 v[126:127], v[128:129], v[192:193]
	v_cndmask_b32_e64 v195, 0, v124, s[0:1]
	v_pk_add_f32 v[124:125], v[130:131], v[134:135]
	v_cndmask_b32_e32 v194, 0, v191, vcc
	v_pk_add_f32 v[124:125], v[124:125], v[126:127]
	v_pk_add_f32 v[126:127], v[132:133], v[136:137]
	v_cvt_pk_bf16_f32 v129, v129, v193
	v_pk_add_f32 v[124:125], v[124:125], v[126:127]
	v_pk_add_f32 v[126:127], v[138:139], v[194:195]
	v_add_u32_e32 v151, 32, v151
	v_pk_add_f32 v[196:197], v[126:127], v[124:125]
	v_cvt_pk_bf16_f32 v126, v132, v136
	v_cvt_pk_bf16_f32 v124, v130, v134
	v_cvt_pk_bf16_f32 v125, v128, v192
	v_cvt_pk_bf16_f32 v128, v131, v135
	v_cvt_pk_bf16_f32 v130, v133, v137
	v_cvt_pk_bf16_f32 v127, v138, v194
	v_cvt_pk_bf16_f32 v131, v139, v195
	s_waitcnt lgkmcnt(0)
	v_mfma_f32_16x16x32_bf16 v[104:107], v[224:227], v[116:119], v[104:107]
	s_add_i32 s4, s4, 64
	v_pk_add_f32 v[160:161], v[160:161], v[196:197]
	s_cmpk_eq_i32 s4, 0x100
	v_mfma_f32_16x16x32_bf16 v[48:51], v[224:227], v[120:123], v[48:51]
	v_mfma_f32_16x16x32_bf16 v[32:35], v[224:227], v[124:127], v[32:35]
	v_mfma_f32_16x16x32_bf16 v[16:19], v[224:227], v[128:131], v[16:19]
	v_mfma_f32_16x16x32_bf16 v[96:99], v[228:231], v[116:119], v[96:99]
	v_mfma_f32_16x16x32_bf16 v[40:43], v[228:231], v[120:123], v[40:43]
	v_mfma_f32_16x16x32_bf16 v[24:27], v[228:231], v[124:127], v[24:27]
	v_mfma_f32_16x16x32_bf16 v[4:7], v[228:231], v[128:131], v[4:7]
	v_mfma_f32_16x16x32_bf16 v[88:91], v[232:235], v[116:119], v[88:91]
	v_mfma_f32_16x16x32_bf16 v[44:47], v[232:235], v[120:123], v[44:47]
	v_mfma_f32_16x16x32_bf16 v[28:31], v[232:235], v[124:127], v[28:31]
	v_mfma_f32_16x16x32_bf16 v[12:15], v[232:235], v[128:131], v[12:15]
	v_mfma_f32_16x16x32_bf16 v[80:83], v[236:239], v[116:119], v[80:83]
	v_mfma_f32_16x16x32_bf16 v[36:39], v[236:239], v[120:123], v[36:39]
	v_mfma_f32_16x16x32_bf16 v[20:23], v[236:239], v[124:127], v[20:23]
	v_mfma_f32_16x16x32_bf16 v[8:11], v[236:239], v[128:131], v[8:11]
	s_cbranch_scc0 .LBB0_587
	s_branch .Latt_exit
; __device__ __forceinline__ void attn_phase(LAS unsigned char* lds, bf16* qkv, const float* qgain, const float* kgain, const float* sink, const float* ropetab, int G, int bid) {
;     ...
;             for (int T = 0; T < 4; ++T) {
;                 bf16x8 kf[2][2];
; #pragma unroll
;                 for (int sub = 0; sub < 2; ++sub)
; #pragma unroll
;                     for (int dh = 0; dh < 2; ++dh) kf[sub][dh] = *(const LAS bf16x8*)(Ks + (T * 32 + sub * 16 + fr) * 160 + dh * 64 + fq * 16);
;                 bf16x8 pb[4];
; #pragma unroll
;                 for (int qi = 0; qi < 4; ++qi) {
;                     f32x4 s0 = (f32x4){0.f, 0.f, 0.f, 0.f}, s1 = (f32x4){0.f, 0.f, 0.f, 0.f};
;                     s0 = __builtin_amdgcn_mfma_f32_16x16x32_bf16(kf[0][0], qf[qi][0], s0, 0, 0, 0);
;                     s0 = __builtin_amdgcn_mfma_f32_16x16x32_bf16(kf[0][1], qf[qi][1], s0, 0, 0, 0);
;                     s1 = __builtin_amdgcn_mfma_f32_16x16x32_bf16(kf[1][0], qf[qi][0], s1, 0, 0, 0);
;                     s1 = __builtin_amdgcn_mfma_f32_16x16x32_bf16(kf[1][1], qf[qi][1], s1, 0, 0, 0);
;                     const int mbase = msg * (T * 32 + fq * 4 - (whalf * 64 + qi * 16 + fr));
;                     float p0[4], p1[4];
; #pragma unroll
;                     for (int j = 0; j < 4; ++j) {
;                         const float e0 = __builtin_amdgcn_exp2f(s0[j] - Mshift), e1 = __builtin_amdgcn_exp2f(s1[j] - Mshift);
;                         p0[j] = (mbase + msg * j >= 0) ? e0 : 0.f;
;                         p1[j] = (mbase + msg * (16 + j) >= 0) ? e1 : 0.f;
;                     }
;                     lsum[qi] += (p0[0] + p0[1]) + (p0[2] + p0[3]) + (p1[0] + p1[1]) + (p1[2] + p1[3]);
;                     u32x4 w; w.x = cvt_pk_bf16(p0[0], p0[1]); w.y = cvt_pk_bf16(p0[2], p0[3]); w.z = cvt_pk_bf16(p1[0], p1[1]); w.w = cvt_pk_bf16(p1[2], p1[3]);
;                     pb[qi] = __builtin_bit_cast(bf16x8, w);
;                 }
; #pragma unroll
;                 for (int dt = 0; dt < 4; ++dt) {
;                     const LAS unsigned char* vp = Vt + (dt * 16 + fr) * 272 + (T * 32 + fq * 4) * 2;
;                     const u32x2 lo = *(const LAS u32x2*)vp, hi = *(const LAS u32x2*)(vp + 32);
;                     u32x4 w; w.x = lo[0]; w.y = lo[1]; w.z = hi[0]; w.w = hi[1];
;                     const bf16x8 vf = __builtin_bit_cast(bf16x8, w);
; #pragma unroll
.LattU_587:
	ds_read_b128 v[124:127], v153
	ds_read_b128 v[128:131], v153 offset:64
	ds_read_b128 v[132:135], v153 offset:2560
	ds_read_b128 v[136:139], v153 offset:2624
	v_add_u32_e32 v240, s4, v186
	ds_read2_b64 v[224:227], v240 offset1:4
	v_add_u32_e32 v241, 0x1000, v240
	ds_read2_b64 v[228:231], v241 offset0:32 offset1:36
	v_add_u32_e32 v241, 0x2000, v240
	ds_read2_b64 v[232:235], v241 offset0:64 offset1:68
	v_add_u32_e32 v241, 0x3000, v240
	ds_read2_b64 v[236:239], v241 offset0:96 offset1:100
	s_waitcnt lgkmcnt(7)
	v_mfma_f32_16x16x32_bf16 v[116:119], v[124:127], v[108:111], 0
	s_waitcnt lgkmcnt(5)
	v_mfma_f32_16x16x32_bf16 v[120:123], v[132:135], v[108:111], 0
	v_add_u32_e32 v153, 0x1400, v153
	v_mfma_f32_16x16x32_bf16 v[116:119], v[128:131], v[112:115], v[116:119]
	s_waitcnt lgkmcnt(4)
	v_mfma_f32_16x16x32_bf16 v[120:123], v[136:139], v[112:115], v[120:123]
	s_nop 5
	v_sub_f32_e32 v116, v116, v174
	v_exp_f32_e32 v191, v116
	v_sub_f32_e32 v116, v120, v174
	v_exp_f32_e32 v192, v116
	v_sub_f32_e32 v116, v117, v174
	v_exp_f32_e32 v194, v116
	v_sub_f32_e32 v116, v121, v174
	v_exp_f32_e32 v196, v116
	v_sub_f32_e32 v116, v118, v174
	v_exp_f32_e32 v198, v116
	v_sub_f32_e32 v116, v122, v174
	v_exp_f32_e32 v200, v116
	v_sub_f32_e32 v116, v119, v174
	v_exp_f32_e32 v202, v116
	v_sub_f32_e32 v116, v123, v174
	v_exp_f32_e32 v204, v116
	v_mfma_f32_16x16x32_bf16 v[116:119], v[124:127], v[68:71], 0
	v_mfma_f32_16x16x32_bf16 v[120:123], v[132:135], v[68:71], 0
	v_mfma_f32_16x16x32_bf16 v[116:119], v[128:131], v[100:103], v[116:119]
	v_mfma_f32_16x16x32_bf16 v[120:123], v[136:139], v[100:103], v[120:123]
	s_nop 6
	v_sub_f32_e32 v116, v116, v174
	v_sub_f32_e32 v120, v120, v174
	v_exp_f32_e32 v116, v116
	v_exp_f32_e32 v193, v120
	v_sub_f32_e32 v120, v121, v174
	v_sub_f32_e32 v117, v117, v174
	v_exp_f32_e32 v195, v120
	v_sub_f32_e32 v120, v122, v174
	v_exp_f32_e32 v117, v117
	v_exp_f32_e32 v199, v120
	v_sub_f32_e32 v120, v123, v174
	v_exp_f32_e32 v203, v120
	v_mov_b32_e32 v121, v116
	v_mov_b32_e32 v120, v191
	v_mov_b32_e32 v123, v193
	v_mov_b32_e32 v193, v117
	v_sub_f32_e32 v118, v118, v174
	v_mov_b32_e32 v122, v192
	v_exp_f32_e32 v118, v118
	v_mov_b32_e32 v192, v194
	v_sub_f32_e32 v119, v119, v174
	v_mov_b32_e32 v195, v195
	v_mov_b32_e32 v194, v196
	v_exp_f32_e32 v119, v119
	v_mov_b32_e32 v197, v118
	v_mov_b32_e32 v196, v198
	v_mov_b32_e32 v199, v199
	v_mov_b32_e32 v198, v200
	v_mov_b32_e32 v201, v119
	v_mov_b32_e32 v200, v202
	v_pk_add_f32 v[116:117], v[120:121], v[192:193]
	v_pk_add_f32 v[118:119], v[196:197], v[200:201]
	v_mov_b32_e32 v203, v203
	v_mov_b32_e32 v202, v204
	v_pk_add_f32 v[116:117], v[116:117], v[118:119]
	v_pk_add_f32 v[118:119], v[122:123], v[194:195]
	s_nop 0
	v_pk_add_f32 v[116:117], v[116:117], v[118:119]
	v_pk_add_f32 v[118:119], v[198:199], v[202:203]
	s_nop 0
	v_pk_add_f32 v[204:205], v[118:119], v[116:117]
	v_cvt_pk_bf16_f32 v116, v120, v192
	v_cvt_pk_bf16_f32 v118, v122, v194
	v_cvt_pk_bf16_f32 v120, v121, v193
	v_cvt_pk_bf16_f32 v122, v123, v195
	v_mfma_f32_16x16x32_bf16 v[192:195], v[124:127], v[60:63], 0
	v_cvt_pk_bf16_f32 v117, v196, v200
	v_cvt_pk_bf16_f32 v119, v198, v202
	v_cvt_pk_bf16_f32 v121, v197, v201
	v_mfma_f32_16x16x32_bf16 v[124:127], v[124:127], v[52:55], 0
	v_cvt_pk_bf16_f32 v123, v199, v203
	v_pk_add_f32 v[170:171], v[170:171], v[204:205]
	v_mfma_f32_16x16x32_bf16 v[198:201], v[128:131], v[64:67], v[192:195]
	v_mfma_f32_16x16x32_bf16 v[128:131], v[128:131], v[56:59], v[124:127]
	v_mfma_f32_16x16x32_bf16 v[124:127], v[132:135], v[52:55], 0
	s_nop 5
	v_sub_f32_e32 v191, v198, v174
	v_exp_f32_e32 v198, v191
	v_mfma_f32_16x16x32_bf16 v[192:195], v[132:135], v[60:63], 0
	v_mfma_f32_16x16x32_bf16 v[132:135], v[136:139], v[56:59], v[124:127]
	v_mfma_f32_16x16x32_bf16 v[202:205], v[136:139], v[64:67], v[192:195]
	s_nop 1
	v_sub_f32_e32 v124, v128, v174
	v_exp_f32_e32 v136, v124
	s_nop 2
	v_sub_f32_e32 v124, v132, v174
	v_exp_f32_e32 v132, v124
	v_sub_f32_e32 v124, v129, v174
	v_exp_f32_e32 v129, v124
	v_sub_f32_e32 v124, v133, v174
	v_sub_f32_e32 v191, v202, v174
	v_exp_f32_e32 v128, v124
	v_sub_f32_e32 v124, v130, v174
	v_exp_f32_e32 v197, v191
	v_sub_f32_e32 v191, v199, v174
	v_exp_f32_e32 v127, v124
	v_sub_f32_e32 v124, v134, v174
	v_exp_f32_e32 v196, v191
	v_sub_f32_e32 v191, v203, v174
	v_exp_f32_e32 v126, v124
	v_sub_f32_e32 v124, v131, v174
	v_exp_f32_e32 v195, v191
	v_sub_f32_e32 v191, v200, v174
	v_exp_f32_e32 v125, v124
	v_sub_f32_e32 v124, v135, v174
	v_mov_b32_e32 v131, v136
	v_mov_b32_e32 v130, v198
	v_mov_b32_e32 v133, v132
	v_mov_b32_e32 v132, v197
	v_mov_b32_e32 v135, v129
	v_mov_b32_e32 v134, v196
	v_exp_f32_e32 v194, v191
	v_sub_f32_e32 v191, v204, v174
	v_mov_b32_e32 v137, v128
	v_exp_f32_e32 v193, v191
	v_mov_b32_e32 v129, v127
	v_sub_f32_e32 v191, v201, v174
	v_mov_b32_e32 v136, v195
	v_exp_f32_e32 v192, v191
	v_mov_b32_e32 v128, v194
	v_mov_b32_e32 v139, v126
	v_sub_f32_e32 v191, v205, v174
	v_exp_f32_e32 v124, v124
	v_exp_f32_e32 v191, v191
	v_mov_b32_e32 v138, v193
	v_mov_b32_e32 v193, v125
	v_mov_b32_e32 v192, v192
	v_pk_add_f32 v[126:127], v[128:129], v[192:193]
	v_mov_b32_e32 v195, v124
	v_pk_add_f32 v[124:125], v[130:131], v[134:135]
	v_mov_b32_e32 v194, v191
	v_pk_add_f32 v[124:125], v[124:125], v[126:127]
	v_pk_add_f32 v[126:127], v[132:133], v[136:137]
	v_cvt_pk_bf16_f32 v129, v129, v193
	v_pk_add_f32 v[124:125], v[124:125], v[126:127]
	v_pk_add_f32 v[126:127], v[138:139], v[194:195]
	v_add_u32_e32 v151, 32, v151
	v_pk_add_f32 v[196:197], v[126:127], v[124:125]
	v_cvt_pk_bf16_f32 v126, v132, v136
	v_cvt_pk_bf16_f32 v124, v130, v134
	v_cvt_pk_bf16_f32 v125, v128, v192
	v_cvt_pk_bf16_f32 v128, v131, v135
	v_cvt_pk_bf16_f32 v130, v133, v137
	v_cvt_pk_bf16_f32 v127, v138, v194
	v_cvt_pk_bf16_f32 v131, v139, v195
	s_waitcnt lgkmcnt(0)
	v_mfma_f32_16x16x32_bf16 v[104:107], v[224:227], v[116:119], v[104:107]
	s_add_i32 s4, s4, 64
	v_pk_add_f32 v[160:161], v[160:161], v[196:197]
	s_cmpk_eq_i32 s4, 0x100
	v_mfma_f32_16x16x32_bf16 v[48:51], v[224:227], v[120:123], v[48:51]
	v_mfma_f32_16x16x32_bf16 v[32:35], v[224:227], v[124:127], v[32:35]
	v_mfma_f32_16x16x32_bf16 v[16:19], v[224:227], v[128:131], v[16:19]
	v_mfma_f32_16x16x32_bf16 v[96:99], v[228:231], v[116:119], v[96:99]
	v_mfma_f32_16x16x32_bf16 v[40:43], v[228:231], v[120:123], v[40:43]
	v_mfma_f32_16x16x32_bf16 v[24:27], v[228:231], v[124:127], v[24:27]
	v_mfma_f32_16x16x32_bf16 v[4:7], v[228:231], v[128:131], v[4:7]
	v_mfma_f32_16x16x32_bf16 v[88:91], v[232:235], v[116:119], v[88:91]
	v_mfma_f32_16x16x32_bf16 v[44:47], v[232:235], v[120:123], v[44:47]
	v_mfma_f32_16x16x32_bf16 v[28:31], v[232:235], v[124:127], v[28:31]
	v_mfma_f32_16x16x32_bf16 v[12:15], v[232:235], v[128:131], v[12:15]
	v_mfma_f32_16x16x32_bf16 v[80:83], v[236:239], v[116:119], v[80:83]
	v_mfma_f32_16x16x32_bf16 v[36:39], v[236:239], v[120:123], v[36:39]
	v_mfma_f32_16x16x32_bf16 v[20:23], v[236:239], v[124:127], v[20:23]
	v_mfma_f32_16x16x32_bf16 v[8:11], v[236:239], v[128:131], v[8:11]
	s_cbranch_scc0 .LattU_587
	s_branch .Latt_exit
; __device__ __forceinline__ void attn_phase(LAS unsigned char* lds, bf16* qkv, const float* qgain, const float* kgain, const float* sink, const float* ropetab, int G, int bid) {
;     ...
;             sb = nsb;
;         }
.Latt_exit:
	s_and_b64 vcc, exec, s[36:37]
	s_cbranch_vccnz .LBB0_560
	s_mov_b32 s18, s17
	s_branch .LBB0_580
